# P3: first GEMM's trailing stage loads prefetch the second GEMM's first K-tiles; second GEMM's prologue loads dropped (one tile per workgroup)
# speedup vs baseline: 1.0202x; 1.0119x over previous
.LBB0_565:
	s_nop 0
	v_cndmask_b32_e64 v0, 0, 1, s[4:5]
	v_cmp_ne_u32_e64 s[0:1], 1, v0
	s_andn2_b64 vcc, exec, s[4:5]
	s_mov_b64 s[4:5], s[24:25]
	s_add_u32 s4, s4, 0x5500000
	s_addc_u32 s5, s5, 0
	s_cbranch_vccnz .LBB0_567
	s_ashr_i32 s4, s51, 31
	s_mul_hi_u32 s5, s10, s51
	s_mul_i32 s4, s10, s4
	s_add_i32 s4, s5, s4
	s_mul_i32 s5, s11, s51
	s_add_i32 s5, s4, s5
	s_mul_i32 s4, s10, s51
	s_add_u32 s4, s44, s4
	s_addc_u32 s5, s45, s5
.LBB0_567:
	s_and_b64 vcc, exec, s[0:1]
	s_mov_b64 s[22:23], s[28:29]
	s_add_u32 s22, s22, 0x200000
	s_addc_u32 s23, s23, 0
	s_cbranch_vccnz .LBB0_569
	s_ashr_i32 s22, s50, 31
	s_mul_hi_u32 s23, s10, s50
	s_mul_i32 s22, s10, s22
	s_add_i32 s22, s23, s22
	s_mul_i32 s23, s11, s50
	s_add_i32 s23, s22, s23
	s_mul_i32 s22, s10, s50
	s_add_u32 s22, s30, s22
	s_addc_u32 s23, s31, s23

.LBB0_579:
	v_readlane_b32 s4, v255, 46
	s_movk_i32 s0, 0x400
	s_add_u32 s48, s91, 0xf00000
	v_readlane_b32 s1, v255, 45
	v_mov_b32_e32 v6, v193
	v_readlane_b32 s5, v255, 47
	s_addc_u32 s49, s1, 0
	s_and_b64 vcc, exec, s[4:5]
	v_readfirstlane_b32 s3, v6
	s_cbranch_vccnz .LBB0_604
	v_lshlrev_b32_e32 v3, 4, v6
	v_add_u32_e32 v0, 0x2000, v3
	v_ashrrev_i32_e32 v1, 31, v0
	v_lshrrev_b32_e32 v1, 22, v1
	v_add_u32_e32 v1, v0, v1
	v_ashrrev_i32_e32 v1, 10, v1
	v_mul_i32_i24_e32 v2, 0x400, v1
	v_sub_u32_e32 v0, v0, v2
	v_lshrrev_b32_e32 v2, 4, v0
	v_bitop3_b32 v2, v2, v0, 32 bitop3:0x6c
	v_ashrrev_i32_e32 v0, 31, v2
	v_lshrrev_b32_e32 v0, 26, v0
	v_add_u32_e32 v4, v2, v0
	v_lshlrev_b32_e32 v5, 3, v1
	v_ashrrev_i32_e32 v0, 6, v4
	v_and_b32_e32 v5, -16, v5
	v_add_u32_e32 v5, v0, v5
	v_and_b32_e32 v0, 3, v0
	s_mov_b32 s4, 0x7fffffe0
	v_lshrrev_b32_e32 v7, 2, v5
	v_lshlrev_b32_e32 v8, 1, v5
	v_and_or_b32 v0, v5, s4, v0
	v_and_b32_e32 v7, 4, v7
	v_and_b32_e32 v8, 24, v8
	v_or3_b32 v0, v0, v7, v8
	v_mul_lo_u32 v7, v0, s0
	v_lshlrev_b32_e32 v0, 5, v1
	v_and_b32_e32 v1, 0xc0, v4
	v_sub_u32_e32 v1, v2, v1
	v_ashrrev_i16_sdwa v1, v242, sext(v1) dst_sel:DWORD dst_unused:UNUSED_PAD src0_sel:DWORD src1_sel:BYTE_0
	v_and_b32_e32 v0, 32, v0
	v_bfe_i32 v1, v1, 0, 16
	v_add_u32_e32 v4, v0, v1
	v_mul_lo_u32 v2, v5, s0
	v_add_lshl_u32 v218, v7, v4, 1
	v_add_lshl_u32 v220, v4, v2, 1
	v_bfe_i32 v4, v6, 27, 1
	v_lshrrev_b32_e32 v4, 22, v4
	v_add_u32_e32 v4, v3, v4
	v_and_b32_e32 v4, 0xfffffc00, v4
	v_sub_u32_e32 v3, v3, v4
	v_lshrrev_b32_e32 v4, 4, v3
	v_ashrrev_i32_e32 v7, 31, v6
	v_bitop3_b32 v4, v4, v3, 32 bitop3:0x6c
	v_lshrrev_b32_e32 v7, 26, v7
	v_ashrrev_i32_e32 v3, 31, v4
	v_add_u32_e32 v7, v6, v7
	v_lshrrev_b32_e32 v3, 26, v3
	v_ashrrev_i32_e32 v7, 6, v7
	v_add_u32_e32 v5, v4, v3
	v_lshlrev_b32_e32 v8, 3, v7
	v_ashrrev_i32_e32 v3, 6, v5
	v_and_b32_e32 v8, -16, v8
	s_ashr_i32 s1, s0, 31
	v_add_u32_e32 v8, v3, v8
	v_and_b32_e32 v3, 3, v3
	s_lshl_b64 s[10:11], s[0:1], 9
	v_and_or_b32 v3, v8, s4, v3
	v_readlane_b32 s4, v254, 62
	v_readlane_b32 s13, v254, 61
	s_mul_i32 s4, s10, s4
	s_mul_hi_u32 s5, s10, s13
	s_add_i32 s12, s5, s4
	s_lshr_b64 s[4:5], s[0:1], 23
	v_readlane_b32 s18, v254, 59
	v_lshrrev_b32_e32 v9, 2, v8
	v_lshlrev_b32_e32 v10, 1, v8
	s_mul_i32 s5, s4, s13
	v_readlane_b32 s19, v254, 60
	v_and_b32_e32 v9, 4, v9
	v_and_b32_e32 v10, 24, v10
	v_and_b32_e32 v5, 0xc0, v5
	s_add_i32 s12, s12, s5
	s_mul_i32 s5, s10, s19
	s_mul_hi_u32 s14, s10, s18
	s_ashr_i32 s6, s3, 6
	v_or3_b32 v3, v3, v9, v10
	v_sub_u32_e32 v4, v4, v5
	s_add_i32 s5, s14, s5
	s_mul_i32 s4, s4, s18
	s_ashr_i32 s7, s3, 8
	s_lshl_b64 s[8:9], s[0:1], 8
	s_lshl_b32 s50, s6, 10
	v_mul_lo_u32 v9, v3, s0
	v_lshlrev_b32_e32 v3, 5, v7
	v_ashrrev_i16_sdwa v4, v242, sext(v4) dst_sel:DWORD dst_unused:UNUSED_PAD src0_sel:DWORD src1_sel:BYTE_0
	s_add_i32 s5, s5, s4
	s_mul_i32 s4, s10, s18
	v_and_b32_e32 v3, 32, v3
	v_bfe_i32 v4, v4, 0, 16
	s_add_u32 s28, s48, s4
	v_add_u32_e32 v7, v3, v4
	s_addc_u32 s29, s49, s5
	s_add_i32 s51, s50, 0
	v_add_lshl_u32 v194, v9, v7, 1
	s_add_i32 m0, s51, 0x10000
	s_mul_i32 s13, s10, s13
	s_add_i32 m0, s51, 0x12000
	s_add_u32 s4, s28, s8
	s_addc_u32 s5, s29, s9
	s_add_i32 m0, s51, 0x14000
	v_mul_lo_u32 v5, v8, s0
	s_add_i32 m0, s51, 0x16000
	s_add_u32 s24, s76, s13
	s_addc_u32 s25, s77, s12
	s_add_i32 s54, s51, 0x2000
	v_add_lshl_u32 v222, v7, v5, 1
	s_mov_b32 m0, s51
	s_add_u32 s12, s24, s8
	s_mov_b32 m0, s54
	s_addc_u32 s13, s25, s9
	s_add_i32 s55, s51, 0x4000
	s_mov_b32 m0, s55
	s_add_i32 s68, s51, 0x6000
	s_mov_b32 m0, s68
	s_cmp_eq_u32 s7, 1
	s_cselect_b64 s[12:13], -1, 0
	s_cmp_lg_u32 s7, 1
	s_cbranch_scc1 .LBB0_582
	s_barrier
.LBB0_582:
	v_bfe_u32 v202, v6, 4, 2
	s_lshr_b32 s1, s1, 26
	v_and_b32_e32 v205, 15, v6
	s_add_i32 s1, s0, s1
	v_lshlrev_b32_e32 v7, 4, v202
	v_lshlrev_b32_e32 v6, 2, v6
	s_ashr_i32 s69, s1, 6
	v_lshl_or_b32 v7, v205, 6, v7
	s_lshl_b32 s1, s7, 13
	v_and_b32_e32 v6, 32, v6
	v_bitop3_b32 v20, v7, s1, v6 bitop3:0xde
	s_lshl_b32 s1, s6, 5
	s_and_b32 s87, s1, 0x60
	v_lshl_add_u64 v[8:9], s[28:29], 0, v[194:195]
	v_mov_b32_e32 v219, v195
	s_lshl_b32 s1, s87, 7
	v_lshl_add_u64 v[10:11], s[28:29], 0, v[218:219]
	v_mov_b32_e32 v223, v195
	v_bitop3_b32 v246, v7, s1, v6 bitop3:0xde
	s_add_i32 m0, s51, 0x18000
	v_lshl_add_u64 v[6:7], v[8:9], 0, s[38:39]
	v_lshl_add_u64 v[16:17], s[24:25], 0, v[222:223]
	v_mov_b32_e32 v221, v195
	s_waitcnt vmcnt(2)
	s_barrier
	v_lshl_add_u64 v[6:7], v[10:11], 0, s[38:39]
	s_add_i32 m0, s51, 0x1a000
	s_add_i32 s88, s51, 0x8000
	v_lshl_add_u64 v[18:19], s[24:25], 0, v[220:221]
	v_lshl_add_u64 v[6:7], v[16:17], 0, s[38:39]
	s_mov_b32 m0, s88
	s_add_i32 s89, s51, 0xa000
	v_lshl_add_u64 v[12:13], s[4:5], 0, v[194:195]
	v_lshl_add_u64 v[6:7], v[18:19], 0, s[38:39]
	s_mov_b32 m0, s89
	v_lshl_add_u64 v[14:15], s[4:5], 0, v[218:219]
	s_add_i32 m0, s51, 0x1c000
	v_lshl_add_u64 v[6:7], v[12:13], 0, s[38:39]
	v_lshl_add_u64 v[6:7], v[14:15], 0, s[38:39]
	s_add_i32 m0, s51, 0x1e000
	s_lshl_b32 s86, s7, 6
	s_cmp_gt_i32 s0, 63
	s_waitcnt vmcnt(6)
	s_cselect_b64 s[14:15], -1, 0
	s_add_i32 s92, s69, -2
	v_add_u32_e32 v3, v5, v3
	v_add_u32_e32 v0, v2, v0
	s_cmpk_lt_u32 s3, 0x100
	v_add_lshl_u32 v4, v3, v4, 1
	v_mov_b32_e32 v5, v195
	v_add_lshl_u32 v0, v0, v1, 1
	v_mov_b32_e32 v1, v195
	s_cselect_b64 s[18:19], -1, 0
	v_lshl_add_u64 v[224:225], s[8:9], 0, v[4:5]
	v_lshl_add_u64 v[226:227], s[8:9], 0, v[0:1]
	s_mov_b32 s96, 0
	v_add_u32_e32 v247, 0, v20
	v_readlane_b32 s7, v254, 58
	v_readlane_b32 s3, v254, 61
	s_barrier
	s_branch .LBB0_585
